# v11 + pass2 state update rescheduled: reads two steps ahead in rotating register sets, one wait per step, no s_nop
# speedup vs baseline: 1.0012x; 1.0012x over previous
.LBB0_1334:
	s_mul_i32 s22, s22, 0xe400
	s_add_i32 s27, s22, 0
	v_add3_u32 v147, s27, v104, v109
	s_add_i32 s29, s27, s19
	ds_read_b64 v[148:149], v147
	ds_read_b64 v[150:151], v147 offset:32
	ds_read_b64 v[152:153], v147 offset:4352
	ds_read_b64 v[154:155], v147 offset:4384
	ds_read_b64 v[196:197], v147 offset:8704
	ds_read_b64 v[198:199], v147 offset:8736
	ds_read_b64 v[200:201], v147 offset:13056
	ds_read_b64 v[202:203], v147 offset:13088
	v_cvt_pk_bf16_f32 v126, v26, v27
	v_cvt_pk_bf16_f32 v127, v28, v29
	v_cvt_pk_bf16_f32 v128, v30, v31
	v_cvt_pk_bf16_f32 v129, v32, v33
	ds_read_b64 v[156:157], v147 offset:64
	ds_read_b64 v[158:159], v147 offset:96
	ds_read_b64 v[160:161], v147 offset:4416
	ds_read_b64 v[162:163], v147 offset:4448
	ds_read_b64 v[204:205], v147 offset:8768
	ds_read_b64 v[206:207], v147 offset:8800
	s_waitcnt lgkmcnt(12)
	v_mfma_f32_16x16x32_bf16 v[62:65], v[126:129], v[148:151], 0
	ds_read_b64 v[208:209], v147 offset:13120
	ds_read_b64 v[210:211], v147 offset:13152
	v_cvt_pk_bf16_f32 v130, v34, v35
	v_cvt_pk_bf16_f32 v131, v36, v37
	v_cvt_pk_bf16_f32 v132, v38, v39
	v_cvt_pk_bf16_f32 v133, v40, v41
	s_waitcnt lgkmcnt(12)
	v_mfma_f32_16x16x32_bf16 v[58:61], v[126:129], v[152:155], 0
	s_waitcnt lgkmcnt(10)
	v_mfma_f32_16x16x32_bf16 v[164:167], v[196:199], v[148:151], 0
	v_mfma_f32_16x16x32_bf16 v[168:171], v[196:199], v[152:155], 0
	s_waitcnt lgkmcnt(8)
	v_mfma_f32_16x16x32_bf16 v[172:175], v[200:203], v[152:155], 0
	ds_read_b64 v[148:149], v147 offset:128
	ds_read_b64 v[150:151], v147 offset:160
	ds_read_b64 v[152:153], v147 offset:4480
	ds_read_b64 v[154:155], v147 offset:4512
	ds_read_b64 v[196:197], v147 offset:8832
	ds_read_b64 v[198:199], v147 offset:8864
	s_waitcnt lgkmcnt(12)
	v_mfma_f32_16x16x32_bf16 v[62:65], v[130:133], v[156:159], v[62:65]
	ds_read_b64 v[200:201], v147 offset:13184
	ds_read_b64 v[202:203], v147 offset:13216
	v_cvt_pk_bf16_f32 v134, v42, v43
	v_cvt_pk_bf16_f32 v135, v44, v45
	v_cvt_pk_bf16_f32 v136, v46, v47
	v_cvt_pk_bf16_f32 v137, v48, v49
	s_waitcnt lgkmcnt(12)
	v_mfma_f32_16x16x32_bf16 v[58:61], v[130:133], v[160:163], v[58:61]
	s_waitcnt lgkmcnt(10)
	v_mfma_f32_16x16x32_bf16 v[164:167], v[204:207], v[156:159], v[164:167]
	v_mfma_f32_16x16x32_bf16 v[168:171], v[204:207], v[160:163], v[168:171]
	s_waitcnt lgkmcnt(8)
	v_mfma_f32_16x16x32_bf16 v[172:175], v[208:211], v[160:163], v[172:175]
	ds_read_b64 v[156:157], v147 offset:192
	ds_read_b64 v[158:159], v147 offset:224
	ds_read_b64 v[160:161], v147 offset:4544
	ds_read_b64 v[162:163], v147 offset:4576
	ds_read_b64 v[204:205], v147 offset:8896
	ds_read_b64 v[206:207], v147 offset:8928
	s_waitcnt lgkmcnt(12)
	v_mfma_f32_16x16x32_bf16 v[62:65], v[134:137], v[148:151], v[62:65]
	ds_read_b64 v[208:209], v147 offset:13248
	ds_read_b64 v[210:211], v147 offset:13280
	v_cvt_pk_bf16_f32 v138, v50, v51
	v_cvt_pk_bf16_f32 v139, v52, v53
	v_cvt_pk_bf16_f32 v140, v54, v55
	v_cvt_pk_bf16_f32 v141, v56, v57
	s_waitcnt lgkmcnt(12)
	v_mfma_f32_16x16x32_bf16 v[58:61], v[134:137], v[152:155], v[58:61]
	s_waitcnt lgkmcnt(10)
	v_mfma_f32_16x16x32_bf16 v[164:167], v[196:199], v[148:151], v[164:167]
	v_mfma_f32_16x16x32_bf16 v[168:171], v[196:199], v[152:155], v[168:171]
	s_waitcnt lgkmcnt(8)
	v_mfma_f32_16x16x32_bf16 v[172:175], v[200:203], v[152:155], v[172:175]
	v_add_u32_e32 v176, s27, v106
	v_add_u32_e32 v68, v176, v123
	ds_read_b64_tr_b16 v[66:67], v68 offset:37888
	ds_read_b64_tr_b16 v[68:69], v68 offset:43008
	s_waitcnt lgkmcnt(8)
	v_mfma_f32_16x16x32_bf16 v[62:65], v[138:141], v[156:159], v[62:65]
	s_waitcnt lgkmcnt(6)
	v_mfma_f32_16x16x32_bf16 v[58:61], v[138:141], v[160:163], v[58:61]
	s_waitcnt lgkmcnt(4)
	v_mfma_f32_16x16x32_bf16 v[164:167], v[204:207], v[156:159], v[164:167]
	v_mfma_f32_16x16x32_bf16 v[168:171], v[204:207], v[160:163], v[168:171]
	s_waitcnt lgkmcnt(2)
	v_mfma_f32_16x16x32_bf16 v[172:175], v[208:211], v[160:163], v[172:175]
	v_add_u32_e32 v125, s27, v105
	v_add_u32_e32 v134, v176, v110
	v_mov_b32_e32 v177, s55
	v_mov_b32_e32 v72, v16
	v_mov_b32_e32 v73, v16
	s_nop 0
	v_cndmask_b32_e64 v165, 0, v165, s[6:7]
	v_cndmask_b32_e64 v166, v166, 0, s[8:9]
	v_cndmask_b32_e64 v167, v167, 0, s[10:11]
	v_cndmask_b32_e64 v164, v164, v177, s[4:5]
	v_cvt_pk_bf16_f32 v70, v164, v165
	v_cvt_pk_bf16_f32 v71, v166, v167
	v_cndmask_b32_e64 v172, v172, v177, s[4:5]
	v_cndmask_b32_e64 v173, v173, 0, s[12:13]
	v_cndmask_b32_e64 v174, v174, 0, s[14:15]
	v_cndmask_b32_e64 v175, v175, 0, s[16:17]
	s_waitcnt lgkmcnt(0)
	v_mfma_f32_16x16x32_bf16 v[62:65], v[66:69], v[70:73], v[62:65]
	v_cvt_pk_bf16_f32 v70, v168, v169
	v_cvt_pk_bf16_f32 v71, v170, v171
	v_cvt_pk_bf16_f32 v72, v172, v173
	v_cvt_pk_bf16_f32 v73, v174, v175
	s_nop 1
	v_mfma_f32_16x16x32_bf16 v[58:61], v[66:69], v[70:73], v[58:61]
	ds_read_b128 v[160:163], v125 offset:56832
	ds_read_b64_tr_b16 v[148:149], v134 offset:27648
	ds_read_b64_tr_b16 v[150:151], v134 offset:32768
	ds_read_b128 v[164:167], v125 offset:56896
	ds_read_b64_tr_b16 v[152:153], v134 offset:27680
	ds_read_b64_tr_b16 v[154:155], v134 offset:32800
	s_waitcnt lgkmcnt(3)
	v_pk_mul_f32 v[26:27], v[26:27], v[160:161]
	v_pk_mul_f32 v[28:29], v[28:29], v[162:163]
	ds_read_b128 v[168:171], v125 offset:56960
	ds_read_b64_tr_b16 v[156:157], v134 offset:27712
	ds_read_b64_tr_b16 v[158:159], v134 offset:32832
	v_mfma_f32_16x16x32_bf16 v[26:29], v[148:151], v[66:69], v[26:29]
	s_waitcnt lgkmcnt(3)
	v_pk_mul_f32 v[30:31], v[30:31], v[164:165]
	v_pk_mul_f32 v[32:33], v[32:33], v[166:167]
	ds_read_b128 v[160:163], v125 offset:57024
	ds_read_b64_tr_b16 v[148:149], v134 offset:27744
	ds_read_b64_tr_b16 v[150:151], v134 offset:32864
	v_mfma_f32_16x16x32_bf16 v[30:33], v[152:155], v[66:69], v[30:33]
	s_waitcnt lgkmcnt(3)
	v_pk_mul_f32 v[34:35], v[34:35], v[168:169]
	v_pk_mul_f32 v[36:37], v[36:37], v[170:171]
	ds_read_b128 v[164:167], v125 offset:57088
	ds_read_b64_tr_b16 v[152:153], v134 offset:27776
	ds_read_b64_tr_b16 v[154:155], v134 offset:32896
	v_mfma_f32_16x16x32_bf16 v[34:37], v[156:159], v[66:69], v[34:37]
	s_waitcnt lgkmcnt(3)
	v_pk_mul_f32 v[38:39], v[38:39], v[160:161]
	v_pk_mul_f32 v[40:41], v[40:41], v[162:163]
	ds_read_b128 v[168:171], v125 offset:57152
	ds_read_b64_tr_b16 v[156:157], v134 offset:27808
	ds_read_b64_tr_b16 v[158:159], v134 offset:32928
	v_mfma_f32_16x16x32_bf16 v[38:41], v[148:151], v[66:69], v[38:41]
	s_waitcnt lgkmcnt(3)
	v_pk_mul_f32 v[42:43], v[42:43], v[164:165]
	v_pk_mul_f32 v[44:45], v[44:45], v[166:167]
	ds_read_b128 v[160:163], v125 offset:57216
	ds_read_b64_tr_b16 v[148:149], v134 offset:27840
	ds_read_b64_tr_b16 v[150:151], v134 offset:32960
	v_mfma_f32_16x16x32_bf16 v[42:45], v[152:155], v[66:69], v[42:45]
	s_waitcnt lgkmcnt(3)
	v_pk_mul_f32 v[46:47], v[46:47], v[168:169]
	v_pk_mul_f32 v[48:49], v[48:49], v[170:171]
	ds_read_b128 v[164:167], v125 offset:57280
	ds_read_b64_tr_b16 v[152:153], v134 offset:27872
	ds_read_b64_tr_b16 v[154:155], v134 offset:32992
	v_mfma_f32_16x16x32_bf16 v[46:49], v[156:159], v[66:69], v[46:49]
	s_waitcnt lgkmcnt(3)
	v_pk_mul_f32 v[50:51], v[50:51], v[160:161]
	v_pk_mul_f32 v[52:53], v[52:53], v[162:163]
	s_nop 1
	v_mfma_f32_16x16x32_bf16 v[50:53], v[148:151], v[66:69], v[50:53]
	s_waitcnt lgkmcnt(0)
	v_pk_mul_f32 v[54:55], v[54:55], v[164:165]
	v_pk_mul_f32 v[56:57], v[56:57], v[166:167]
	s_nop 1
	v_mfma_f32_16x16x32_bf16 v[54:57], v[152:155], v[66:69], v[54:57]
	v_mul_f32_e32 v148, v62, v62
	v_mul_f32_e32 v149, v58, v58
	v_fmac_f32_e32 v148, v63, v63
	v_fmac_f32_e32 v149, v59, v59
	v_fmac_f32_e32 v148, v64, v64
	v_fmac_f32_e32 v149, v60, v60
	v_fmac_f32_e32 v148, v65, v65
	v_fmac_f32_e32 v149, v61, v61
	v_lshl_add_u32 v156, v77, 5, s29
	s_nop 0
	v_permlane16_swap_b32_e32 v148, v149
	v_add_f32_e32 v148, v148, v149
	v_mov_b32_e32 v149, v148
	s_nop 1
	v_permlane32_swap_b32_e32 v148, v149
	v_add_f32_e32 v148, v148, v149
	s_mov_b64 s[22:23], exec
	s_mov_b32 exec_hi, 0
	ds_write_b32 v156, v148 offset:57344
	s_mov_b64 exec, s[22:23]
	s_waitcnt lgkmcnt(0)
	s_barrier
	s_andn2_b64 vcc, exec, s[20:21]
	s_cbranch_vccnz .LBB0_1330
	v_add3_u32 v68, s28, v96, v120
	ds_read_b64_tr_b16 v[66:67], v68 offset:17408
	ds_read_b64_tr_b16 v[68:69], v68 offset:18688
	v_add_u32_e32 v138, s28, v236
	v_add3_u32 v139, s28, v109, v222
	ds_read_b64 v[180:181], v138 offset:17408
	ds_read_b64 v[182:183], v138 offset:22528
	ds_read_b64 v[184:185], v139
	ds_read_b64 v[186:187], v139 offset:4352
	s_waitcnt lgkmcnt(4)
	v_mfma_f32_16x16x32_bf16 v[70:73], v[66:69], v[4:7], 0
	v_mfma_f32_16x16x32_bf16 v[66:69], v[66:69], v[0:3], 0
	s_mov_b32 s23, 0x42e60000
	s_waitcnt lgkmcnt(0)
	v_lshlrev_b32_e32 v188, 16, v180
	v_and_b32_e32 v189, 0xffff0000, v180
	v_lshlrev_b32_e32 v190, 16, v181
	v_and_b32_e32 v191, 0xffff0000, v181
	v_lshlrev_b32_e32 v192, 16, v182
	v_and_b32_e32 v193, 0xffff0000, v182
	v_lshlrev_b32_e32 v194, 16, v183
	v_and_b32_e32 v195, 0xffff0000, v183
	v_lshlrev_b32_e32 v196, 16, v184
	v_and_b32_e32 v197, 0xffff0000, v184
	v_lshlrev_b32_e32 v198, 16, v185
	v_and_b32_e32 v199, 0xffff0000, v185
	v_lshlrev_b32_e32 v200, 16, v186
	v_and_b32_e32 v201, 0xffff0000, v186
	v_lshlrev_b32_e32 v202, 16, v187
	v_and_b32_e32 v203, 0xffff0000, v187
	v_exp_f32_e32 v188, v188
	v_exp_f32_e32 v189, v189
	v_exp_f32_e32 v190, v190
	v_exp_f32_e32 v191, v191
	v_exp_f32_e32 v192, v192
	v_exp_f32_e32 v193, v193
	v_exp_f32_e32 v194, v194
	v_exp_f32_e32 v195, v195
	v_sub_f32_e32 v188, 1.0, v188
	v_sub_f32_e32 v189, 1.0, v189
	v_sub_f32_e32 v190, 1.0, v190
	v_sub_f32_e32 v191, 1.0, v191
	v_sub_f32_e32 v192, 1.0, v192
	v_sub_f32_e32 v193, 1.0, v193
	v_sub_f32_e32 v194, 1.0, v194
	v_sub_f32_e32 v195, 1.0, v195
	v_exp_f32_e32 v204, v70
	v_exp_f32_e32 v205, v71
	v_exp_f32_e32 v206, v72
	v_exp_f32_e32 v207, v73
	v_exp_f32_e32 v208, v66
	v_exp_f32_e32 v209, v67
	v_exp_f32_e32 v210, v68
	v_exp_f32_e32 v211, v69
	v_sub_f32_dpp v126, v66, v70 row_newbcast:15 row_mask:0xf bank_mask:0xf
	v_sub_f32_dpp v127, v67, v71 row_newbcast:15 row_mask:0xf bank_mask:0xf
	v_sub_f32_dpp v128, v68, v72 row_newbcast:15 row_mask:0xf bank_mask:0xf
	v_sub_f32_dpp v129, v69, v73 row_newbcast:15 row_mask:0xf bank_mask:0xf
	v_sub_f32_dpp v130, v66, v66 row_newbcast:15 row_mask:0xf bank_mask:0xf
	v_sub_f32_dpp v131, v67, v67 row_newbcast:15 row_mask:0xf bank_mask:0xf
	v_sub_f32_dpp v132, v68, v68 row_newbcast:15 row_mask:0xf bank_mask:0xf
	v_sub_f32_dpp v133, v69, v69 row_newbcast:15 row_mask:0xf bank_mask:0xf
	v_mul_f32_e32 v196, v196, v204
	v_mul_f32_e32 v197, v197, v205
	v_mul_f32_e32 v198, v198, v206
	v_mul_f32_e32 v199, v199, v207
	v_mul_f32_e32 v200, v200, v208
	v_mul_f32_e32 v201, v201, v209
	v_mul_f32_e32 v202, v202, v210
	v_mul_f32_e32 v203, v203, v211
	v_min_f32_e64 v204, -v70, s23
	v_min_f32_e64 v205, -v71, s23
	v_min_f32_e64 v206, -v72, s23
	v_min_f32_e64 v207, -v73, s23
	v_min_f32_e64 v208, -v66, s23
	v_min_f32_e64 v209, -v67, s23
	v_min_f32_e64 v210, -v68, s23
	v_min_f32_e64 v211, -v69, s23
	v_exp_f32_e32 v126, v126
	v_exp_f32_e32 v127, v127
	v_exp_f32_e32 v128, v128
	v_exp_f32_e32 v129, v129
	v_exp_f32_e32 v130, v130
	v_exp_f32_e32 v131, v131
	v_exp_f32_e32 v132, v132
	v_exp_f32_e32 v133, v133
	v_exp_f32_e32 v204, v204
	v_exp_f32_e32 v205, v205
	v_exp_f32_e32 v206, v206
	v_exp_f32_e32 v207, v207
	v_exp_f32_e32 v208, v208
	v_exp_f32_e32 v209, v209
	v_exp_f32_e32 v210, v210
	v_exp_f32_e32 v211, v211
	v_exp_f32_e32 v212, v66
	v_exp_f32_e32 v213, v67
	v_exp_f32_e32 v214, v68
	v_exp_f32_e32 v215, v69
	v_mul_f32_e32 v126, v126, v188
	v_mul_f32_e32 v127, v127, v189
	v_mul_f32_e32 v128, v128, v190
	v_mul_f32_e32 v129, v129, v191
	v_mul_f32_e32 v130, v130, v192
	v_mul_f32_e32 v131, v131, v193
	v_mul_f32_e32 v132, v132, v194
	v_mul_f32_e32 v133, v133, v195
	v_mul_f32_e32 v204, v204, v188
	v_mul_f32_e32 v205, v205, v189
	v_mul_f32_e32 v206, v206, v190
	v_mul_f32_e32 v207, v207, v191
	v_mul_f32_e32 v208, v208, v192
	v_mul_f32_e32 v209, v209, v193
	v_mul_f32_e32 v210, v210, v194
	v_mul_f32_e32 v211, v211, v195
	v_lshl_add_u32 v216, v222, 1, s28
	v_cvt_pk_bf16_f32 v180, v196, v197
	v_cvt_pk_bf16_f32 v181, v198, v199
	v_cvt_pk_bf16_f32 v182, v200, v201
	v_cvt_pk_bf16_f32 v183, v202, v203
	v_cvt_pk_bf16_f32 v184, v204, v205
	v_cvt_pk_bf16_f32 v185, v206, v207
	v_cvt_pk_bf16_f32 v186, v208, v209
	v_cvt_pk_bf16_f32 v187, v210, v211
	v_cvt_pk_bf16_f32 v134, v126, v127
	v_cvt_pk_bf16_f32 v135, v128, v129
	v_cvt_pk_bf16_f32 v136, v130, v131
	v_cvt_pk_bf16_f32 v137, v132, v133
	ds_write_b64 v139, v[180:181]
	ds_write_b64 v139, v[182:183] offset:4352
	ds_write_b64 v139, v[184:185] offset:8704
	ds_write_b64 v139, v[186:187] offset:13056
	ds_write_b64 v138, v[134:135] offset:27648
	ds_write_b64 v138, v[136:137] offset:32768
	s_and_saveexec_b64 s[20:21], s[2:3]
	ds_write_b128 v216, v[212:215] offset:56832
	s_branch .LBB0_1329
